# sample recurrences: norm-weight loads hoisted before the state stores so end-of-item waits are counted (no vmcnt(0) drain); phase-2 copy-1 entry-path waits replaced by one drain before the loop
# speedup vs baseline: 1.0155x; 1.0062x over previous
; template <int DK, int MODE>
; __device__ void rec_sample_loop(const Params& p, unsigned char* smem, const int rep) {
;   constexpr int SET_FLOATS = 8 * DK + 8 * DK + 512 + 64 + 4096 + 64 + (DK * 8 + 64 * 8) / 2;
;   const int tid = (int)p.tidx, lane = tid & 63, w = tid >> 6;
;   const int l15 = lane & 15, g = lane >> 4;
;   constexpr int CPR = DK / 8;
;   constexpr int DPW = DK / 8;
;   constexpr int NB = DPW / 16;
;   const int dbase = w * DPW;
;   const int pitch = (MODE == 0) ? 512 : 64;
;   int vz;
;   asm volatile("v_mov_b32 %0, 0" : "=v"(vz));
;   const u16* src = ((MODE == 0) ? (const u16*)(p.ws + OFF_PROJ) : (const u16*)(p.ws + OFF_XBCC)) + vz;
;   const int sstride = (MODE == 0) ? PROJ_LD : 4096;
;   const u16* gsrc = (const u16*)(p.ws + OFF_PROJ) + vz;
;   const float* dtv = (const float*)(p.ws + OFF_DT) + vz;
;   const float* cumv = (const float*)(p.ws + OFF_CUM) + vz;
;   u16* aout = (u16*)(p.ws + OFF_A2);
;   float* parts = (float*)(p.ws + OFF_PARTS);
;   u32x4 rqk[2] = {(u32x4){0u, 0u, 0u, 0u}, (u32x4){0u, 0u, 0u, 0u}}, rv[2] = {(u32x4){0u, 0u, 0u, 0u}, (u32x4){0u, 0u, 0u, 0u}};
;   f32x4 sv[2][NB][4];
;   u16 gzs[2] = {0, 0};
;   float pcu[2] = {0.f, 0.f}, pvc[2] = {0.f, 0.f}, pvu[2] = {1.f, 1.f}, pvl[2] = {0.f, 0.f};
;   const int nitems = 4096 * rep;
;   const int G = (int)gridDim.x;
;   if ((int)blockIdx.x < nitems) SAMPLE_ISSUE(0, ((int)blockIdx.x & 4095) + vz)
;   for (int itb = blockIdx.x; itb < nitems; itb += 2 * G) {
.LBB0_454:
	v_add_u32_sdwa v43, v96, v97 dst_sel:DWORD dst_unused:UNUSED_PAD src0_sel:DWORD src1_sel:BYTE_3
	v_and_b32_e32 v43, 0xffffff00, v43
	v_sub_u32_e32 v43, v96, v43
	v_ashrrev_i16_e32 v45, 15, v43
	v_lshrrev_b16_e32 v45, 11, v45
	v_lshlrev_b32_e32 v40, 2, v50
	v_add_u16_e32 v46, v43, v45
	v_or_b32_e32 v42, v40, v93
	v_ashrrev_i16_e32 v45, 5, v46
	v_and_b32_e32 v46, 0xffffffe0, v46
	v_sub_u16_e32 v43, v43, v46
	v_or_b32_e32 v46, 1, v42
	v_ashrrev_i32_e32 v47, 31, v46
	v_lshlrev_b64 v[98:99], 11, v[46:47]
	v_or_b32_e32 v46, 2, v42
	v_ashrrev_i32_e32 v47, 31, v46
	v_lshlrev_b64 v[100:101], 11, v[46:47]
	v_or_b32_e32 v46, 3, v42
	v_ashrrev_i32_e32 v47, 31, v46
	v_bfe_i32 v52, v43, 0, 16
	v_lshlrev_b32_e32 v43, 3, v96
	v_lshlrev_b64 v[102:103], 11, v[46:47]
	v_or_b32_e32 v46, 16, v42
	s_add_u32 s82, s0, 0x11262000
	v_ashrrev_i32_e32 v87, 3, v96
	v_and_b32_e32 v92, 56, v43
	v_mov_b32_e32 v43, 10
	v_ashrrev_i32_e32 v47, 31, v46
	s_addc_u32 s83, s1, 0
	v_lshlrev_b32_sdwa v53, v43, sext(v45) dst_sel:DWORD dst_unused:UNUSED_PAD src0_sel:DWORD src1_sel:WORD_0
	v_sub_u32_e32 v43, 7, v87
	v_lshlrev_b64 v[104:105], 11, v[46:47]
	v_or_b32_e32 v46, 17, v42
	s_add_u32 s94, s0, 0x15662000
	s_movk_i32 s0, 0x200
	v_cvt_f32_u32_e32 v162, v43
	v_ashrrev_i32_e32 v43, 31, v42
	v_ashrrev_i32_e32 v47, 31, v46
	v_cmp_gt_i32_e64 s[2:3], s0, v96
	v_add_u32_e32 v51, 0xff, v96
	v_cmp_gt_i32_e64 s[6:7], 64, v96
	v_cmp_lt_i32_e64 s[8:9], 63, v96
	v_and_b32_e32 v94, 63, v96
	v_cmp_gt_u32_e64 s[10:11], 64, v96
	v_and_b32_e32 v58, 0x3fffffc0, v96
	v_lshlrev_b64 v[96:97], 11, v[42:43]
	v_lshlrev_b64 v[106:107], 11, v[46:47]
	v_or_b32_e32 v46, 18, v42
	v_or_b32_e32 v42, 19, v42
	s_movk_i32 s22, 0x1ff
	v_ashrrev_i32_e32 v43, 31, v42
	v_lshlrev_b64 v[110:111], 11, v[42:43]
	v_mov_b32_e32 v42, 0x2000
	v_cmp_gt_u32_e64 s[22:23], s22, v51
	v_ashrrev_i32_e32 v47, 31, v46
	v_lshlrev_b64 v[108:109], 11, v[46:47]
	v_cndmask_b32_e64 v42, v42, 0, s[22:23]
	v_add_u32_e32 v46, v42, v53
	v_mov_b32_e32 v42, 1
	v_and_b32_e32 v55, 56, v146
	v_lshlrev_b32_sdwa v42, v42, sext(v45) dst_sel:DWORD dst_unused:UNUSED_PAD src0_sel:DWORD src1_sel:WORD_0
	v_lshl_add_u32 v164, v52, 7, v42
	v_lshlrev_b32_e32 v42, 2, v55
	v_lshl_or_b32 v165, v87, 8, v42
	v_lshlrev_b32_e32 v42, 1, v87
	v_or_b32_e32 v43, 1, v40
	v_lshl_add_u32 v166, v55, 4, v42
	v_lshlrev_b32_e32 v42, 10, v160
	v_cmp_gt_u32_e64 s[44:45], v49, v40
	v_cmp_gt_u32_e64 s[46:47], v49, v43
	v_lshlrev_b32_e32 v170, 5, v43
	v_or_b32_e32 v43, 2, v40
	v_or_b32_e32 v40, 3, v40
	v_and_b32_e32 v42, 0x1c00, v42
	v_cmp_gt_u32_e64 s[48:49], v49, v43
	v_lshlrev_b32_e32 v171, 5, v43
	v_cmp_gt_u32_e64 s[50:51], v49, v40
	v_lshlrev_b32_e32 v172, 5, v40
	v_lshlrev_b32_e32 v40, 2, v93
	v_lshlrev_b32_e32 v43, 4, v50
	v_add3_u32 v175, v42, v40, v43
	v_lshlrev_b32_e32 v40, 10, v50
	v_lshl_add_u32 v176, v161, 11, v40
	v_and_b32_e32 v40, 64, v160
	s_movk_i32 s0, 0x1fe
	v_cmp_gt_u32_e64 s[12:13], 32, v95
	v_cmp_gt_u32_e32 vcc, 8, v49
	v_lshl_add_u32 v167, v50, 5, v42
	v_add_u32_e32 v40, 64, v40
	v_xor_b32_e32 v42, 32, v160
	s_addc_u32 s95, s1, 0
	v_cmp_lt_u32_e64 s[4:5], s0, v51
	s_and_b64 s[0:1], s[12:13], vcc
	v_cmp_lt_i32_e32 vcc, v42, v40
	v_writelane_b32 v255, s76, 9
	v_cmp_eq_u32_e64 s[26:27], 0, v49
	v_cndmask_b32_e32 v42, v160, v42, vcc
	v_lshlrev_b32_e32 v179, 2, v42
	v_xor_b32_e32 v42, 16, v160
	v_cmp_lt_i32_e32 vcc, v42, v40
	v_writelane_b32 v255, s77, 10
	v_writelane_b32 v255, s26, 11
	v_cndmask_b32_e32 v42, v160, v42, vcc
	v_lshlrev_b32_e32 v180, 2, v42
	v_xor_b32_e32 v42, 8, v160
	v_cmp_lt_i32_e32 vcc, v42, v40
	v_writelane_b32 v255, s27, 12
	v_cmp_eq_u32_e64 s[26:27], 1, v49
	v_cndmask_b32_e32 v42, v160, v42, vcc
	v_lshlrev_b32_e32 v181, 2, v42
	v_xor_b32_e32 v42, 4, v160
	v_cmp_lt_i32_e32 vcc, v42, v40
	v_writelane_b32 v255, s26, 13
	v_lshlrev_b32_e32 v168, 2, v49
	v_cndmask_b32_e32 v42, v160, v42, vcc
	v_lshlrev_b32_e32 v182, 2, v42
	v_xor_b32_e32 v42, 2, v160
	v_cmp_lt_i32_e32 vcc, v42, v40
	v_writelane_b32 v255, s27, 14
	v_cmp_eq_u32_e64 s[26:27], 2, v49
	v_cndmask_b32_e32 v42, v160, v42, vcc
	v_lshlrev_b32_e32 v183, 2, v42
	v_xor_b32_e32 v42, 1, v160
	v_cmp_lt_i32_e32 vcc, v42, v40
	v_writelane_b32 v255, s26, 15
	v_mov_b32_e32 v41, 0
	v_cndmask_b32_e32 v40, v160, v42, vcc
	v_writelane_b32 v255, s27, 16
	v_cmp_eq_u32_e64 s[26:27], 3, v49
	v_lshlrev_b32_e32 v184, 2, v40
	v_mov_b32_e32 v40, 0xbe00
	v_mov_b32_e32 v42, 0x9e00
	v_writelane_b32 v255, s26, 17
	v_mad_u32_u24 v174, v49, 12, v168
	v_cndmask_b32_e64 v40, v40, v42, s[22:23]
	v_lshlrev_b32_e32 v54, 5, v52
	v_or_b32_e32 v56, v49, v93
	v_lshlrev_b32_e32 v57, 4, v49
	v_cmp_lt_u32_e64 s[16:17], 7, v49
	s_lshl_b32 s91, s96, 1
	v_writelane_b32 v255, s27, 18
	v_cmp_eq_u32_e64 s[26:27], 4, v49
	v_cmp_eq_u32_e64 s[36:37], 5, v49
	v_cmp_eq_u32_e64 s[38:39], 6, v49
	v_cmp_eq_u32_e64 s[40:41], 7, v49
	v_mad_i32_i24 v47, v49, -12, v174
	v_lshlrev_b32_e32 v177, 2, v95
	v_add_u32_e32 v49, v40, v53
	v_mov_b32_e32 v42, v41
	v_mov_b32_e32 v43, v41
	v_lshlrev_b32_e32 v90, 3, v52
	v_writelane_b32 v255, s26, 19
	v_cmp_eq_u32_e64 s[42:43], 1, v50
	v_lshlrev_b32_e32 v169, 7, v50
	v_lshl_add_u32 v178, v58, 2, v177
	s_mov_b32 s31, s78
	s_add_u32 s24, s24, 0x5400000
	v_mov_b32_e32 v40, v41
	v_add_u32_e32 v188, v46, v54
	v_lshlrev_b32_e32 v112, 2, v48
	v_add_u32_e32 v189, v49, v54
	v_add_u32_e32 v196, v47, v176
	v_mov_b64_e32 v[48:49], v[42:43]
	v_mov_b64_e32 v[52:53], v[42:43]
	v_ashrrev_i32_e32 v91, 31, v90
	v_cmp_gt_u32_e64 s[14:15], 16, v95
	v_add_u32_e32 v163, 0x4000, v161
	v_cmp_gt_u32_e64 s[18:19], 2, v95
	v_cmp_eq_u32_e64 s[20:21], 0, v95
	v_writelane_b32 v255, s27, 20
	v_lshlrev_b32_e32 v173, 4, v56
	v_cmp_eq_u32_e64 s[52:53], 1, v161
	v_cmp_eq_u32_e64 s[54:55], 2, v161
	v_cmp_eq_u32_e64 s[56:57], 3, v161
	v_cmp_eq_u32_e64 s[58:59], 4, v161
	v_cmp_eq_u32_e64 s[60:61], 5, v161
	v_cmp_eq_u32_e64 s[62:63], 6, v161
	v_cmp_eq_u32_e64 s[64:65], 7, v161
	v_cmp_lt_i32_e64 s[66:67], -1, v161
	v_cmp_lt_i32_e64 s[68:69], 0, v161
	v_cmp_lt_i32_e64 s[70:71], 1, v161
	v_cmp_lt_i32_e64 s[72:73], 2, v161
	v_cmp_lt_i32_e64 s[74:75], 3, v161
	v_cmp_lt_i32_e64 s[76:77], 4, v161
	v_cmp_lt_i32_e64 s[78:79], 5, v161
	v_cmp_lt_i32_e64 s[80:81], 6, v161
	v_add_u32_e32 v185, 0x12800, v164
	v_add_u32_e32 v186, 0x13800, v166
	v_add_u32_e32 v187, 0xe700, v178
	s_addc_u32 s25, s25, 0
	s_movk_i32 s87, 0x3080
	s_mov_b32 s33, 0xc2fc0000
	s_mov_b32 s30, 0x800000
	v_lshlrev_b32_e32 v114, 1, v94
	v_add_u32_e32 v190, 0x13800, v57
	v_mov_b32_e32 v191, 0x4000
	v_mov_b32_e32 v192, 0x42800000
	v_not_b32_e32 v193, 63
	v_mov_b32_e32 v195, 0x42000000
	v_mov_b64_e32 v[46:47], v[40:41]
	v_mov_b64_e32 v[50:51], v[40:41]
	v_mov_b32_e32 v197, 0
	s_mov_b32 s35, s31
	s_waitcnt vmcnt(0)
	s_branch .LBB0_456

; __device__ __forceinline__ float bf2f(u16 h) { return __uint_as_float(((uint32_t)h) << 16); }
; __device__ __forceinline__ float ex2(float x) { return __builtin_amdgcn_exp2f(x); }
; template <int DK, int MODE>
; __device__ void rec_sample_loop(const Params& p, unsigned char* smem, const int rep) {
;     ...
;     const float lgh = (MODE == 0) ? log2f(1.0f - exp2f(-5.0f - (float)h)) : 0.f;
;     if (tid < 2 * DK) {
;       const int which = tid / DK, c = tid % DK;
;       float* dst = (which ? kS : qS) + (c / CPR) * DK + (c % CPR) * 8;
;       dst[0] = bf2f((u16)(rqkc.x & 0xffff)); dst[1] = bf2f((u16)(rqkc.x >> 16));
;       dst[2] = bf2f((u16)(rqkc.y & 0xffff)); dst[3] = bf2f((u16)(rqkc.y >> 16));
;       dst[4] = bf2f((u16)(rqkc.z & 0xffff)); dst[5] = bf2f((u16)(rqkc.z >> 16));
;       dst[6] = bf2f((u16)(rqkc.w & 0xffff)); dst[7] = bf2f((u16)(rqkc.w >> 16));
;       if (which) {
;         u16* dT = kTb + ((c % CPR) * 8) * 8 + (c / CPR);
;         dT[0 * 8] = (u16)(rqkc.x & 0xffff); dT[1 * 8] = (u16)(rqkc.x >> 16);
;         dT[2 * 8] = (u16)(rqkc.y & 0xffff); dT[3 * 8] = (u16)(rqkc.y >> 16);
;         dT[4 * 8] = (u16)(rqkc.z & 0xffff); dT[5 * 8] = (u16)(rqkc.z >> 16);
;         dT[6 * 8] = (u16)(rqkc.w & 0xffff); dT[7 * 8] = (u16)(rqkc.w >> 16);
;       }
;     }
;     if (tid < 64) {
;       const int t = tid >> 3, kc = tid & 7;
;       float vv[8];
;       vv[0] = bf2f((u16)(rvc.x & 0xffff)); vv[1] = bf2f((u16)(rvc.x >> 16));
;       vv[2] = bf2f((u16)(rvc.y & 0xffff)); vv[3] = bf2f((u16)(rvc.y >> 16));
;       vv[4] = bf2f((u16)(rvc.z & 0xffff)); vv[5] = bf2f((u16)(rvc.z >> 16));
;       vv[6] = bf2f((u16)(rvc.w & 0xffff)); vv[7] = bf2f((u16)(rvc.w >> 16));
;       float* dst = vS + t * 64 + kc * 8;
;       const float wt = (MODE == 0) ? ex2((float)(7 - t) * lgh) : pvu[par] * ex2(pvl[par] - pvc[par]);
;       u16* dT = vwTb + (kc * 8) * 8 + t;
; #pragma unroll
;       for (int x = 0; x < 8; ++x) { dst[x] = vv[x]; dT[x * 8] = f2bf(vv[x] * wt); }
;     }
.LBB0_462:
	s_and_saveexec_b64 vcc, s[2:3]
	s_cbranch_execz .LBB0_465
	s_nop 0
	v_and_b32_e32 v55, 0xffff0000, v0
	v_lshlrev_b32_e32 v54, 16, v0
	v_and_b32_e32 v57, 0xffff0000, v1
	v_lshlrev_b32_e32 v56, 16, v1
	ds_write_b128 v188, v[54:57]
	v_and_b32_e32 v55, 0xffff0000, v2
	v_lshlrev_b32_e32 v54, 16, v2
	v_and_b32_e32 v57, 0xffff0000, v3
	v_lshlrev_b32_e32 v56, 16, v3
	ds_write_b128 v188, v[54:57] offset:16
	s_and_b64 exec, exec, s[4:5]
	s_cbranch_execz .LBB0_465
	ds_write_b16 v164, v0 offset:35328
	ds_write_b16_d16_hi v164, v0 offset:35344
	ds_write_b16 v164, v1 offset:35360
	ds_write_b16_d16_hi v164, v1 offset:35376
	ds_write_b16 v164, v2 offset:35392
	ds_write_b16_d16_hi v164, v2 offset:35408
	ds_write_b16 v164, v3 offset:35424
	ds_write_b16_d16_hi v164, v3 offset:35440
.LBB0_465:
	s_or_b64 exec, exec, vcc
	s_and_b32 s28, s31, 0xfff
	v_add_u32_e32 v40, s28, v86
	v_bfe_u32 v198, v40, 3, 2
	v_cvt_f32_ubyte0_e32 v54, v198
	v_sub_f32_e32 v54, 0xc0a00000, v54
	v_cmp_gt_f32_e32 vcc, s33, v54
	s_nop 1
	v_cndmask_b32_e32 v55, 0, v192, vcc
	v_add_f32_e32 v54, v54, v55
	v_exp_f32_e32 v54, v54
	v_cndmask_b32_e32 v55, 0, v193, vcc
	v_ldexp_f32 v54, v54, v55
	v_sub_f32_e32 v54, 1.0, v54
	v_cmp_gt_f32_e32 vcc, s30, v54
	s_nop 1
	v_cndmask_b32_e64 v55, 0, 32, vcc
	v_ldexp_f32 v54, v54, v55
	v_log_f32_e32 v54, v54
	v_cndmask_b32_e32 v55, 0, v195, vcc
	v_sub_f32_e32 v115, v54, v55
	s_and_saveexec_b64 vcc, s[6:7]
	s_cbranch_execz .LBB0_467
	v_mul_f32_e32 v54, v115, v162
	v_exp_f32_e32 v58, v54
	s_nop 0
	v_lshlrev_b32_e32 v54, 16, v36
	v_and_b32_e32 v55, 0xffff0000, v36
	v_mul_f32_e32 v56, v58, v54
	v_mul_f32_e32 v57, v58, v55
	v_cvt_pk_bf16_f32 v56, v56, s0
	ds_write_b16 v166, v56 offset:39424
	v_cvt_pk_bf16_f32 v56, v57, s0
	ds_write_b16 v166, v56 offset:39440
	v_lshlrev_b32_e32 v56, 16, v37
	s_waitcnt lgkmcnt(2)
	v_mul_f32_e32 v59, v58, v56
	v_and_b32_e32 v57, 0xffff0000, v37
	v_cvt_pk_bf16_f32 v59, v59, s0
	ds_write_b16 v166, v59 offset:39456
	ds_write_b128 v165, v[54:57] offset:16384
	v_mul_f32_e32 v54, v58, v57
	v_cvt_pk_bf16_f32 v54, v54, s0
	ds_write_b16 v166, v54 offset:39472
	v_lshlrev_b32_e32 v54, 16, v38
	v_mul_f32_e32 v56, v58, v54
	v_and_b32_e32 v55, 0xffff0000, v38
	v_cvt_pk_bf16_f32 v56, v56, s0
	ds_write_b16 v166, v56 offset:39488
	v_mul_f32_e32 v56, v58, v55
	v_cvt_pk_bf16_f32 v56, v56, s0
	ds_write_b16 v166, v56 offset:39504
	v_lshlrev_b32_e32 v56, 16, v39
	v_mul_f32_e32 v59, v58, v56
	v_and_b32_e32 v57, 0xffff0000, v39
	v_cvt_pk_bf16_f32 v59, v59, s0
	ds_write_b16 v166, v59 offset:39520
	ds_write_b128 v165, v[54:57] offset:16400
	v_mul_f32_e32 v54, v58, v57
	v_cvt_pk_bf16_f32 v54, v54, s0
	ds_write_b16 v166, v54 offset:39536

; template <int DK, int MODE>
; __device__ void rec_sample_loop(const Params& p, unsigned char* smem, const int rep) {
;     ...
;       const bf16x8 zero8 = (bf16x8){0, 0, 0, 0, 0, 0, 0, 0};
;       bf16x8 kA[NB], vB[4], qa;
; #pragma unroll
;       for (int db = 0; db < NB; ++db) {
;         const bf16x8 t8 = *(const bf16x8*)(kTb + (dbase + 16 * db + l15) * 8);
;         kA[db] = (g == 0) ? t8 : zero8;
;       }
; #pragma unroll
;       for (int eb = 0; eb < 4; ++eb) {
;         const bf16x8 t8 = *(const bf16x8*)(vwTb + (16 * eb + l15) * 8);
;         vB[eb] = (g == 0) ? t8 : zero8;
;       }
;       {
;         const float* qrow = qS + (l15 & 7) * DK + dbase + 4 * g;
;         const float4 q0 = *(const float4*)qrow;
;         float4 q1 = make_float4(0.f, 0.f, 0.f, 0.f);
;         if (NB == 2) q1 = *(const float4*)(qrow + 16);
;         u32x4 qq;
;         qq.x = pack2(q0.x, q0.y); qq.y = pack2(q0.z, q0.w); qq.z = pack2(q1.x, q1.y); qq.w = pack2(q1.z, q1.w);
;         if (l15 >= 8) qq = (u32x4){0u, 0u, 0u, 0u};
;         qa = __builtin_bit_cast(bf16x8, qq);
;       }
; #pragma unroll
;       for (int eb = 0; eb < 4; ++eb) {
;         u32x4 sb;
;         sb.x = pack2(sv[par][0][eb][0], sv[par][0][eb][1]);
;         sb.y = pack2(sv[par][0][eb][2], sv[par][0][eb][3]);
;         if (NB == 2) {
;           sb.z = pack2(sv[par][NB - 1][eb][0], sv[par][NB - 1][eb][1]);
;           sb.w = pack2(sv[par][NB - 1][eb][2], sv[par][NB - 1][eb][3]);
;         } else { sb.z = 0u; sb.w = 0u; }
;         const f32x4 o3 = __builtin_amdgcn_mfma_f32_16x16x32_bf16(qa, __builtin_bit_cast(bf16x8, sb),
;                                                                  (f32x4){0.f, 0.f, 0.f, 0.f}, 0, 0, 0);
;         if (g < 2) {
; #pragma unroll
;           for (int r = 0; r < 4; ++r) redS[(w * 8 + 4 * g + r) * 64 + 16 * eb + l15] = o3[r];
;         }
; #pragma unroll
;         for (int db = 0; db < NB; ++db) {
;           f32x4 c = sv[par][db][eb];
;           c[0] *= atot; c[1] *= atot; c[2] *= atot; c[3] *= atot;
;           const f32x4 dn = __builtin_amdgcn_mfma_f32_16x16x32_bf16(kA[db], vB[eb], c, 0, 0, 0);
; #pragma unroll
;           for (int r = 0; r < 4; ++r) s1[(size_t)(dbase + 16 * db + 4 * g + r) * pitch + 16 * eb + l15] = dn[r];
;         }
;       }
.LBB0_470:
	s_or_b64 exec, exec, vcc
	ds_read_b128 v[62:65], v173 offset:35328
	ds_read_b128 v[70:73], v173 offset:35584
	ds_read_b128 v[58:61], v175
	ds_read_b128 v[78:81], v174 offset:39424
	ds_read_b128 v[74:77], v174 offset:39680
	ds_read_b128 v[82:85], v175 offset:64
	ds_read_b128 v[66:69], v174 offset:39936
	ds_read_b128 v[54:57], v174 offset:40192
	s_waitcnt lgkmcnt(5)
	v_cvt_pk_bf16_f32 v58, v58, v59
	v_cvt_pk_bf16_f32 v59, v60, v61
	s_waitcnt lgkmcnt(2)
	v_cvt_pk_bf16_f32 v60, v82, v83
	v_cvt_pk_bf16_f32 v61, v84, v85
	v_cndmask_b32_e64 v61, v61, 0, s[16:17]
	v_cndmask_b32_e64 v60, v60, 0, s[16:17]
	v_cndmask_b32_e64 v59, v59, 0, s[16:17]
	v_cndmask_b32_e64 v58, v58, 0, s[16:17]
	s_nop 0
	v_cvt_pk_bf16_f32 v82, v4, v5
	s_nop 0
	v_cvt_pk_bf16_f32 v83, v6, v7
	s_nop 0
	v_cvt_pk_bf16_f32 v84, v20, v21
	s_nop 0
	v_cvt_pk_bf16_f32 v85, v22, v23
	s_nop 1
	v_mfma_f32_16x16x32_bf16 v[82:85], v[58:61], v[82:85], 0
	s_and_saveexec_b64 s[28:29], s[12:13]
	s_cbranch_execz .LBB0_472
	s_nop 5
	ds_write2st64_b32 v196, v82, v83 offset0:73 offset1:74
	ds_write2st64_b32 v196, v84, v85 offset0:75 offset1:76
.LBB0_472:
	s_or_b64 exec, exec, s[28:29]
	v_ashrrev_i32_e32 v206, 5, v40
	s_nop 3
	v_lshl_or_b32 v82, v206, 2, v198
	v_ashrrev_i32_e32 v83, 31, v82
	v_and_b32_e32 v205, 7, v40
	v_lshlrev_b64 v[82:83], 19, v[82:83]
	v_lshl_add_u64 v[82:83], s[24:25], 0, v[82:83]
	v_lshlrev_b32_e32 v40, 8, v205
	v_lshl_add_u64 v[84:85], v[82:83], 0, v[40:41]
	v_lshlrev_b32_e32 v212, 9, v198
	v_lshlrev_b32_e32 v213, 6, v205
	v_or3_b32 v212, v213, v95, v212
	v_mov_b32_e32 v213, 0
	v_lshl_add_u64 v[212:213], v[212:213], 2, s[92:93]
	global_load_dword v214, v[212:213], off
	v_exp_f32_e32 v82, v113
	v_cndmask_b32_e64 v65, 0, v65, s[14:15]
	v_cndmask_b32_e64 v64, 0, v64, s[14:15]
	v_cndmask_b32_e64 v63, 0, v63, s[14:15]
	v_cndmask_b32_e64 v62, 0, v62, s[14:15]
	v_cndmask_b32_e64 v73, 0, v73, s[14:15]
	v_cndmask_b32_e64 v72, 0, v72, s[14:15]
	v_cndmask_b32_e64 v71, 0, v71, s[14:15]
	v_cndmask_b32_e64 v70, 0, v70, s[14:15]
	v_cndmask_b32_e64 v81, 0, v81, s[14:15]
	v_cndmask_b32_e64 v80, 0, v80, s[14:15]
	v_cndmask_b32_e64 v79, 0, v79, s[14:15]
	v_cndmask_b32_e64 v78, 0, v78, s[14:15]
	v_pk_mul_f32 v[148:149], v[6:7], v[82:83] op_sel_hi:[1,0]
	v_pk_mul_f32 v[146:147], v[4:5], v[82:83] op_sel_hi:[1,0]
	v_mov_b32_e32 v113, v41
	v_pk_mul_f32 v[156:157], v[22:23], v[82:83] op_sel_hi:[1,0]
	v_mfma_f32_16x16x32_bf16 v[148:151], v[62:65], v[78:81], v[146:149]
	v_mul_f32_e64 v154, v20, v82
	v_mul_f32_e64 v155, v21, v82
	v_lshl_add_u64 v[158:159], v[84:85], 0, v[112:113]
	v_lshl_add_u64 v[84:85], v[158:159], 0, v[96:97]
	v_mfma_f32_16x16x32_bf16 v[78:81], v[70:73], v[78:81], v[154:157]
	v_lshl_add_u64 v[146:147], v[158:159], 0, v[98:99]
	s_nop 1
	global_store_dword v[84:85], v148, off
	global_store_dword v[146:147], v149, off
	v_lshl_add_u64 v[148:149], v[158:159], 0, v[100:101]
	v_lshl_add_u64 v[152:153], v[158:159], 0, v[102:103]
	global_store_dword v[148:149], v150, off
	global_store_dword v[152:153], v151, off
	v_lshl_add_u64 v[150:151], v[158:159], 0, v[104:105]
	v_lshl_add_u64 v[154:155], v[158:159], 0, v[106:107]
	v_lshl_add_u64 v[156:157], v[158:159], 0, v[108:109]
	v_lshl_add_u64 v[158:159], v[158:159], 0, v[110:111]
	global_store_dword v[150:151], v78, off
	global_store_dword v[154:155], v79, off
	global_store_dword v[156:157], v80, off
	global_store_dword v[158:159], v81, off
	v_cvt_pk_bf16_f32 v78, v8, v9
	v_cvt_pk_bf16_f32 v79, v10, v11
	v_cvt_pk_bf16_f32 v80, v24, v25
	s_nop 0
	v_cvt_pk_bf16_f32 v81, v26, v27
	s_nop 1
	v_mfma_f32_16x16x32_bf16 v[78:81], v[58:61], v[78:81], 0
	s_and_saveexec_b64 s[28:29], s[12:13]
	s_cbranch_execz .LBB0_474
	v_add_u32_e32 v40, 64, v196
	s_nop 4
	ds_write2st64_b32 v40, v78, v79 offset0:73 offset1:74
	ds_write2st64_b32 v40, v80, v81 offset0:75 offset1:76
.LBB0_474:
	s_or_b64 exec, exec, s[28:29]
	v_mov_b32_e32 v83, v82
	s_nop 3
	v_mov_b32_e32 v78, v82
	v_mov_b32_e32 v79, v82
	v_cndmask_b32_e64 v77, 0, v77, s[14:15]
	v_cndmask_b32_e64 v76, 0, v76, s[14:15]
	v_cndmask_b32_e64 v75, 0, v75, s[14:15]
	v_cndmask_b32_e64 v74, 0, v74, s[14:15]
	v_pk_mul_f32 v[210:211], v[10:11], v[78:79]
	v_pk_mul_f32 v[208:209], v[8:9], v[82:83]
	s_nop 1
	v_mfma_f32_16x16x32_bf16 v[208:211], v[62:65], v[74:77], v[208:211]
	s_nop 7
	global_store_dword v[84:85], v208, off offset:64
	global_store_dword v[146:147], v209, off offset:64
	global_store_dword v[148:149], v210, off offset:64
	global_store_dword v[152:153], v211, off offset:64
	v_pk_mul_f32 v[210:211], v[26:27], v[78:79]
	v_pk_mul_f32 v[208:209], v[24:25], v[82:83]
	s_nop 1
	v_mfma_f32_16x16x32_bf16 v[74:77], v[70:73], v[74:77], v[208:211]
	s_nop 7
	global_store_dword v[150:151], v74, off offset:64
	global_store_dword v[154:155], v75, off offset:64
	global_store_dword v[156:157], v76, off offset:64
	global_store_dword v[158:159], v77, off offset:64
	v_cvt_pk_bf16_f32 v74, v12, v13
	v_cvt_pk_bf16_f32 v75, v14, v15
	v_cvt_pk_bf16_f32 v76, v28, v29
	s_nop 0
	v_cvt_pk_bf16_f32 v77, v30, v31
	s_nop 1
	v_mfma_f32_16x16x32_bf16 v[74:77], v[58:61], v[74:77], 0
	s_and_saveexec_b64 s[28:29], s[12:13]
	s_cbranch_execz .LBB0_476
	v_add_u32_e32 v40, 0x80, v196
	s_nop 4
	ds_write2st64_b32 v40, v74, v75 offset0:73 offset1:74
	ds_write2st64_b32 v40, v76, v77 offset0:75 offset1:76
.LBB0_476:
	s_or_b64 exec, exec, s[28:29]
	s_waitcnt lgkmcnt(1)
	v_cndmask_b32_e64 v69, 0, v69, s[14:15]
	v_cndmask_b32_e64 v68, 0, v68, s[14:15]
	v_cndmask_b32_e64 v67, 0, v67, s[14:15]
	v_cndmask_b32_e64 v66, 0, v66, s[14:15]
	v_pk_mul_f32 v[76:77], v[14:15], v[78:79]
	v_pk_mul_f32 v[74:75], v[12:13], v[82:83]
	s_nop 1
	v_mfma_f32_16x16x32_bf16 v[74:77], v[62:65], v[66:69], v[74:77]
	s_nop 7
	global_store_dword v[84:85], v74, off offset:128
	global_store_dword v[146:147], v75, off offset:128
	global_store_dword v[148:149], v76, off offset:128
	global_store_dword v[152:153], v77, off offset:128
	v_pk_mul_f32 v[76:77], v[30:31], v[78:79]
	v_pk_mul_f32 v[74:75], v[28:29], v[82:83]
	s_nop 1
	v_mfma_f32_16x16x32_bf16 v[66:69], v[70:73], v[66:69], v[74:77]
	s_nop 7
	global_store_dword v[150:151], v66, off offset:128
	global_store_dword v[154:155], v67, off offset:128
	global_store_dword v[156:157], v68, off offset:128
	global_store_dword v[158:159], v69, off offset:128
	v_cvt_pk_bf16_f32 v66, v16, v17
	v_cvt_pk_bf16_f32 v67, v18, v19
	v_cvt_pk_bf16_f32 v68, v32, v33
	s_nop 0
	v_cvt_pk_bf16_f32 v69, v34, v35
	s_nop 1
	v_mfma_f32_16x16x32_bf16 v[58:61], v[58:61], v[66:69], 0
	s_and_saveexec_b64 s[28:29], s[12:13]
	s_cbranch_execz .LBB0_478
	v_add_u32_e32 v40, 0xc0, v196
	s_nop 4
	ds_write2st64_b32 v40, v58, v59 offset0:73 offset1:74
	ds_write2st64_b32 v40, v60, v61 offset0:75 offset1:76

; __device__ __forceinline__ float bf2f(u16 h) { return __uint_as_float(((uint32_t)h) << 16); }
; __device__ __forceinline__ float ex2(float x) { return __builtin_amdgcn_exp2f(x); }
; __device__ __forceinline__ float silu(float x) { return x * __builtin_amdgcn_rcpf(1.0f + __expf(-x)); }
; template <int DK, int MODE>
; __device__ void rec_sample_loop(const Params& p, unsigned char* smem, const int rep) {
;     ...
;     {
;       const int i = w, e = lane;
;       float o = 0.f;
; #pragma unroll
;       for (int ww = 0; ww < 8; ++ww) o += redS[(ww * 8 + i) * 64 + e];
;       float ci = 0.f;
; #pragma unroll
;       for (int t = 0; t < 8; ++t) if (t == i) ci = cum[t];
;       o *= ex2(ci);
; #pragma unroll
;       for (int jj = 0; jj < 8; ++jj) if (jj <= i) o += scS[i * 8 + jj] * vS[jj * 64 + e];
;       const int row = row0 + i;
;       const float gv = bf2f(gzv);
;       if (MODE == 0) {
;         const float ssq = wave_sum(o * o);
;         const float val = o * p.ret_head_norm[h * 512 + s * 64 + e] * silu(gv);
;         aout[(size_t)row * 2048 + h * 512 + s * 64 + e] = f2bf(val);
;         if (lane < 2) parts[(size_t)row * 64 + h * 16 + s * 2 + lane] = lane == 0 ? ssq : 0.f;
.LBB0_494:
	s_or_b64 exec, exec, s[28:29]
	v_mul_f32_e32 v40, v55, v55
	ds_bpermute_b32 v40, v179, v40
	v_lshlrev_b32_e32 v64, 6, v205
	s_waitcnt vmcnt(32)
	v_lshlrev_b32_e32 v60, 16, v44
	v_lshl_add_u32 v56, v206, 3, v163
	v_ashrrev_i32_e32 v57, 31, v56
	s_waitcnt lgkmcnt(0)
	v_fmac_f32_e32 v40, v55, v55
	ds_bpermute_b32 v54, v180, v40
	v_mov_b32_e32 v115, v41
	s_waitcnt lgkmcnt(0)
	v_add_f32_e32 v40, v40, v54
	ds_bpermute_b32 v54, v181, v40
	s_waitcnt lgkmcnt(0)
	v_add_f32_e32 v40, v40, v54
	ds_bpermute_b32 v54, v182, v40
	s_waitcnt lgkmcnt(0)
	v_add_f32_e32 v40, v40, v54
	ds_bpermute_b32 v54, v183, v40
	s_waitcnt lgkmcnt(0)
	v_add_f32_e32 v58, v40, v54
	v_lshlrev_b32_e32 v40, 9, v198
	v_or3_b32 v40, v64, v95, v40
	v_lshl_add_u64 v[62:63], v[40:41], 2, s[92:93]
	v_mul_f32_e32 v40, 0xbfb8aa3b, v60
	v_exp_f32_e32 v40, v40
	ds_bpermute_b32 v59, v184, v58
	v_add_f32_e32 v40, 1.0, v40
	v_rcp_f32_e32 v54, v40
	s_waitcnt vmcnt(32)
	v_mov_b32_e32 v61, v214
	v_pk_mul_f32 v[54:55], v[54:55], v[60:61]
	s_nop 0
	v_mul_f32_e32 v40, v54, v55
	v_lshlrev_b64 v[54:55], 12, v[56:57]
	v_cvt_pk_bf16_f32 v60, v40, s0
	v_lshl_add_u64 v[54:55], s[82:83], 0, v[54:55]
	v_lshlrev_b32_e32 v40, 10, v198
	v_lshl_add_u64 v[54:55], v[54:55], 0, v[40:41]
	v_lshlrev_b32_e32 v40, 1, v64
	v_lshl_add_u64 v[54:55], v[54:55], 0, v[40:41]
	v_lshl_add_u64 v[54:55], v[54:55], 0, v[114:115]
	global_store_short v[54:55], v60, off
	s_and_saveexec_b64 s[28:29], s[18:19]
	s_cbranch_execz .LBB0_496
	s_waitcnt lgkmcnt(0)
	v_add_f32_e32 v40, v58, v59
	v_lshlrev_b64 v[54:55], 8, v[56:57]
	v_cndmask_b32_e64 v58, 0, v40, s[20:21]
	v_lshl_add_u64 v[54:55], s[94:95], 0, v[54:55]
	v_lshlrev_b32_e32 v40, 6, v198
	v_lshl_add_u64 v[54:55], v[54:55], 0, v[40:41]
	v_lshlrev_b32_e32 v40, 3, v205
	v_lshl_add_u64 v[54:55], v[54:55], 0, v[40:41]
	v_lshlrev_b32_e32 v40, 2, v94
	v_lshl_add_u64 v[54:55], v[54:55], 0, v[40:41]
	global_store_dword v[54:55], v58, off

; __device__ __forceinline__ float silu(float x) { return x * __builtin_amdgcn_rcpf(1.0f + __expf(-x)); }
; template <int DK, int MODE>
; __device__ void rec_sample_loop(const Params& p, unsigned char* smem, const int rep) {
;     ...
;       for (int eb = 0; eb < 4; ++eb) {
;         u32x4 sb;
;         sb.x = pack2(sv[par][0][eb][0], sv[par][0][eb][1]);
;         sb.y = pack2(sv[par][0][eb][2], sv[par][0][eb][3]);
;         if (NB == 2) {
;           sb.z = pack2(sv[par][NB - 1][eb][0], sv[par][NB - 1][eb][1]);
;           sb.w = pack2(sv[par][NB - 1][eb][2], sv[par][NB - 1][eb][3]);
;         } else { sb.z = 0u; sb.w = 0u; }
;         const f32x4 o3 = __builtin_amdgcn_mfma_f32_16x16x32_bf16(qa, __builtin_bit_cast(bf16x8, sb),
;                                                                  (f32x4){0.f, 0.f, 0.f, 0.f}, 0, 0, 0);
;         if (g < 2) {
; #pragma unroll
;           for (int r = 0; r < 4; ++r) redS[(w * 8 + 4 * g + r) * 64 + 16 * eb + l15] = o3[r];
;         }
; #pragma unroll
;         for (int db = 0; db < NB; ++db) {
;           f32x4 c = sv[par][db][eb];
;           c[0] *= atot; c[1] *= atot; c[2] *= atot; c[3] *= atot;
;           const f32x4 dn = __builtin_amdgcn_mfma_f32_16x16x32_bf16(kA[db], vB[eb], c, 0, 0, 0);
; #pragma unroll
;           for (int r = 0; r < 4; ++r) s1[(size_t)(dbase + 16 * db + 4 * g + r) * pitch + 16 * eb + l15] = dn[r];
;         }
;       }
;     ...
;         const float val = o * p.ret_head_norm[h * 512 + s * 64 + e] * silu(gv);
.LBB0_516:
	s_or_b64 exec, exec, s[26:27]
	v_ashrrev_i32_e32 v206, 5, v40
	s_nop 3
	v_lshl_or_b32 v82, v206, 2, v198
	v_ashrrev_i32_e32 v83, 31, v82
	v_and_b32_e32 v205, 7, v40
	v_lshlrev_b64 v[82:83], 19, v[82:83]
	v_lshl_add_u64 v[82:83], s[24:25], 0, v[82:83]
	v_lshlrev_b32_e32 v40, 8, v205
	v_lshl_add_u64 v[84:85], v[82:83], 0, v[40:41]
	v_lshlrev_b32_e32 v212, 9, v198
	v_lshlrev_b32_e32 v213, 6, v205
	v_or3_b32 v212, v213, v95, v212
	v_mov_b32_e32 v213, 0
	v_lshl_add_u64 v[212:213], v[212:213], 2, s[92:93]
	global_load_dword v214, v[212:213], off
	v_exp_f32_e32 v82, v113
	v_cndmask_b32_e64 v65, 0, v65, s[14:15]
	v_cndmask_b32_e64 v64, 0, v64, s[14:15]
	v_cndmask_b32_e64 v63, 0, v63, s[14:15]
	v_cndmask_b32_e64 v62, 0, v62, s[14:15]
	v_cndmask_b32_e64 v73, 0, v73, s[14:15]
	v_cndmask_b32_e64 v72, 0, v72, s[14:15]
	v_cndmask_b32_e64 v71, 0, v71, s[14:15]
	v_cndmask_b32_e64 v70, 0, v70, s[14:15]
	v_cndmask_b32_e64 v81, 0, v81, s[14:15]
	v_cndmask_b32_e64 v80, 0, v80, s[14:15]
	v_cndmask_b32_e64 v79, 0, v79, s[14:15]
	v_cndmask_b32_e64 v78, 0, v78, s[14:15]
	v_pk_mul_f32 v[148:149], v[82:83], v[130:131] op_sel_hi:[0,1]
	v_pk_mul_f32 v[146:147], v[82:83], v[120:121] op_sel_hi:[0,1]
	v_mov_b32_e32 v113, v41
	v_pk_mul_f32 v[156:157], v[82:83], v[138:139] op_sel_hi:[0,1]
	v_mfma_f32_16x16x32_bf16 v[148:151], v[62:65], v[78:81], v[146:149]
	v_mul_f32_e64 v154, v82, v128
	v_mul_f32_e64 v155, v82, v129
	v_lshl_add_u64 v[158:159], v[84:85], 0, v[112:113]
	v_lshl_add_u64 v[84:85], v[158:159], 0, v[96:97]
	v_mfma_f32_16x16x32_bf16 v[78:81], v[70:73], v[78:81], v[154:157]
	v_lshl_add_u64 v[146:147], v[158:159], 0, v[98:99]
	s_nop 1
	global_store_dword v[84:85], v148, off
	global_store_dword v[146:147], v149, off
	v_lshl_add_u64 v[148:149], v[158:159], 0, v[100:101]
	v_lshl_add_u64 v[152:153], v[158:159], 0, v[102:103]
	global_store_dword v[148:149], v150, off
	global_store_dword v[152:153], v151, off
	v_lshl_add_u64 v[150:151], v[158:159], 0, v[104:105]
	v_lshl_add_u64 v[154:155], v[158:159], 0, v[106:107]
	v_lshl_add_u64 v[156:157], v[158:159], 0, v[108:109]
	v_lshl_add_u64 v[158:159], v[158:159], 0, v[110:111]
	global_store_dword v[150:151], v78, off
	global_store_dword v[154:155], v79, off
	global_store_dword v[156:157], v80, off
	global_store_dword v[158:159], v81, off
	v_cvt_pk_bf16_f32 v78, v116, v117
	v_cvt_pk_bf16_f32 v79, v132, v133
	v_cvt_pk_bf16_f32 v80, v124, v125
	v_cvt_pk_bf16_f32 v81, v140, v141
	s_nop 1
	v_mfma_f32_16x16x32_bf16 v[78:81], v[58:61], v[78:81], 0
	s_and_saveexec_b64 s[26:27], s[12:13]
	s_cbranch_execz .LBB0_518
	v_add_u32_e32 v40, 64, v207
	s_nop 4
	ds_write2st64_b32 v40, v78, v79 offset0:231 offset1:232
	ds_write2st64_b32 v40, v80, v81 offset0:233 offset1:234

; __device__ __forceinline__ float bf2f(u16 h) { return __uint_as_float(((uint32_t)h) << 16); }
; __device__ __forceinline__ float ex2(float x) { return __builtin_amdgcn_exp2f(x); }
; __device__ __forceinline__ float silu(float x) { return x * __builtin_amdgcn_rcpf(1.0f + __expf(-x)); }
; template <int DK, int MODE>
; __device__ void rec_sample_loop(const Params& p, unsigned char* smem, const int rep) {
;     ...
;     {
;       const int i = w, e = lane;
;       float o = 0.f;
; #pragma unroll
;       for (int ww = 0; ww < 8; ++ww) o += redS[(ww * 8 + i) * 64 + e];
;       float ci = 0.f;
; #pragma unroll
;       for (int t = 0; t < 8; ++t) if (t == i) ci = cum[t];
;       o *= ex2(ci);
; #pragma unroll
;       for (int jj = 0; jj < 8; ++jj) if (jj <= i) o += scS[i * 8 + jj] * vS[jj * 64 + e];
;       const int row = row0 + i;
;       const float gv = bf2f(gzv);
;       if (MODE == 0) {
;         const float ssq = wave_sum(o * o);
;         const float val = o * p.ret_head_norm[h * 512 + s * 64 + e] * silu(gv);
;         aout[(size_t)row * 2048 + h * 512 + s * 64 + e] = f2bf(val);
;         if (lane < 2) parts[(size_t)row * 64 + h * 16 + s * 2 + lane] = lane == 0 ? ssq : 0.f;
.LBB0_538:
	s_or_b64 exec, exec, s[26:27]
	v_mul_f32_e32 v40, v55, v55
	ds_bpermute_b32 v40, v179, v40
	v_lshlrev_b32_e32 v64, 6, v205
	v_lshlrev_b32_e32 v60, 16, v197
	v_lshl_add_u32 v56, v206, 3, v163
	v_ashrrev_i32_e32 v57, 31, v56
	s_waitcnt lgkmcnt(0)
	v_fmac_f32_e32 v40, v55, v55
	ds_bpermute_b32 v54, v180, v40
	v_mov_b32_e32 v115, v41
	s_waitcnt lgkmcnt(0)
	v_add_f32_e32 v40, v40, v54
	ds_bpermute_b32 v54, v181, v40
	s_waitcnt lgkmcnt(0)
	v_add_f32_e32 v40, v40, v54
	ds_bpermute_b32 v54, v182, v40
	s_waitcnt lgkmcnt(0)
	v_add_f32_e32 v40, v40, v54
	ds_bpermute_b32 v54, v183, v40
	s_waitcnt lgkmcnt(0)
	v_add_f32_e32 v58, v40, v54
	v_lshlrev_b32_e32 v40, 9, v198
	v_or3_b32 v40, v64, v95, v40
	v_lshl_add_u64 v[62:63], v[40:41], 2, s[92:93]
	v_mul_f32_e32 v40, 0xbfb8aa3b, v60
	v_exp_f32_e32 v40, v40
	ds_bpermute_b32 v59, v184, v58
	v_add_f32_e32 v40, 1.0, v40
	v_rcp_f32_e32 v54, v40
	s_waitcnt vmcnt(32)
	v_mov_b32_e32 v61, v214
	v_pk_mul_f32 v[54:55], v[54:55], v[60:61]
	s_nop 0
	v_mul_f32_e32 v40, v54, v55
	v_lshlrev_b64 v[54:55], 12, v[56:57]
	v_cvt_pk_bf16_f32 v60, v40, s0
	v_lshl_add_u64 v[54:55], s[82:83], 0, v[54:55]
	v_lshlrev_b32_e32 v40, 10, v198
	v_lshl_add_u64 v[54:55], v[54:55], 0, v[40:41]
	v_lshlrev_b32_e32 v40, 1, v64
	v_lshl_add_u64 v[54:55], v[54:55], 0, v[40:41]
	v_lshl_add_u64 v[54:55], v[54:55], 0, v[114:115]
	global_store_short v[54:55], v60, off
	s_and_saveexec_b64 s[26:27], s[18:19]
	s_cbranch_execz .LBB0_455
	s_waitcnt lgkmcnt(0)
	v_add_f32_e32 v40, v58, v59
	v_lshlrev_b64 v[54:55], 8, v[56:57]
	v_cndmask_b32_e64 v58, 0, v40, s[20:21]
	v_lshl_add_u64 v[54:55], s[94:95], 0, v[54:55]
	v_lshlrev_b32_e32 v40, 6, v198
	v_lshl_add_u64 v[54:55], v[54:55], 0, v[40:41]
	v_lshlrev_b32_e32 v40, 3, v205
	v_lshl_add_u64 v[54:55], v[54:55], 0, v[40:41]
	v_lshlrev_b32_e32 v40, 2, v94
	v_lshl_add_u64 v[54:55], v[54:55], 0, v[40:41]
	global_store_dword v[54:55], v58, off
	s_branch .LBB0_455

; template <int DK, int MODE>
; __device__ void rec_sample_loop(const Params& p, unsigned char* smem, const int rep) {
;     ...
;       for (int eb = 0; eb < 4; ++eb) {
;         u32x4 sb;
;         sb.x = pack2(sv[par][0][eb][0], sv[par][0][eb][1]);
;         sb.y = pack2(sv[par][0][eb][2], sv[par][0][eb][3]);
;         if (NB == 2) {
;           sb.z = pack2(sv[par][NB - 1][eb][0], sv[par][NB - 1][eb][1]);
;           sb.w = pack2(sv[par][NB - 1][eb][2], sv[par][NB - 1][eb][3]);
;         } else { sb.z = 0u; sb.w = 0u; }
;         const f32x4 o3 = __builtin_amdgcn_mfma_f32_16x16x32_bf16(qa, __builtin_bit_cast(bf16x8, sb),
;                                                                  (f32x4){0.f, 0.f, 0.f, 0.f}, 0, 0, 0);
;         if (g < 2) {
; #pragma unroll
;           for (int r = 0; r < 4; ++r) redS[(w * 8 + 4 * g + r) * 64 + 16 * eb + l15] = o3[r];
;         }
; #pragma unroll
;         for (int db = 0; db < NB; ++db) {
;           f32x4 c = sv[par][db][eb];
;           c[0] *= atot; c[1] *= atot; c[2] *= atot; c[3] *= atot;
;           const f32x4 dn = __builtin_amdgcn_mfma_f32_16x16x32_bf16(kA[db], vB[eb], c, 0, 0, 0);
; #pragma unroll
;           for (int r = 0; r < 4; ++r) s1[(size_t)(dbase + 16 * db + 4 * g + r) * pitch + 16 * eb + l15] = dn[r];
;         }
;       }
.LBB0_1771:
	s_or_b64 exec, exec, s[48:49]
	s_and_b32 s48, s89, 0xfff
	s_nop 3
	v_exp_f32_e32 v70, v43
	s_waitcnt lgkmcnt(3)
	v_cndmask_b32_e64 v55, 0, v55, s[16:17]
	v_cndmask_b32_e64 v54, 0, v54, s[16:17]
	v_cndmask_b32_e64 v53, 0, v53, s[16:17]
	v_cndmask_b32_e64 v52, 0, v52, s[16:17]
	v_add_u32_e32 v68, s48, v74
	v_ashrrev_i32_e32 v69, 31, v68
	v_and_b32_e32 v212, 31, v68
	v_lshlrev_b32_e32 v213, 2, v212
	global_load_dword v214, v213, s[92:93]
	v_lshl_or_b32 v216, v212, 6, v87
	v_mov_b32_e32 v217, 0
	v_lshl_add_u64 v[216:217], v[216:217], 2, s[94:95]
	global_load_dword v215, v[216:217], off
	v_lshlrev_b64 v[120:121], 15, v[68:69]
	v_lshl_add_u64 v[126:127], v[98:99], 0, v[120:121]
	v_pk_mul_f32 v[122:123], v[6:7], v[70:71] op_sel_hi:[1,0]
	v_pk_mul_f32 v[120:121], v[4:5], v[70:71] op_sel_hi:[1,0]
	s_waitcnt lgkmcnt(2)
	v_cndmask_b32_e64 v67, 0, v67, s[16:17]
	v_cndmask_b32_e64 v66, 0, v66, s[16:17]
	v_cndmask_b32_e64 v65, 0, v65, s[16:17]
	v_cndmask_b32_e64 v64, 0, v64, s[16:17]
	v_lshl_add_u64 v[124:125], v[126:127], 0, v[92:93]
	s_nop 0
	v_mfma_f32_16x16x32_bf16 v[64:67], v[52:55], v[64:67], v[120:123]
	s_nop 2
	v_lshl_add_u64 v[120:121], v[126:127], 0, v[88:89]
	v_lshl_add_u64 v[122:123], v[126:127], 0, v[90:91]
	v_lshl_add_u64 v[126:127], v[126:127], 0, v[94:95]
	s_nop 1
	global_store_dword v[120:121], v64, off
	global_store_dword v[122:123], v65, off
	global_store_dword v[124:125], v66, off
	global_store_dword v[126:127], v67, off
	v_cvt_pk_bf16_f32 v64, v8, v9
	v_cvt_pk_bf16_f32 v65, v10, v11
	v_mov_b32_e32 v66, v30
	v_mov_b32_e32 v67, v30
	s_nop 1
	v_mfma_f32_16x16x32_bf16 v[64:67], v[28:31], v[64:67], 0
	s_and_saveexec_b64 s[48:49], s[14:15]
	s_cbranch_execz .LBB0_1773
	v_add_u32_e32 v43, 64, v159
	s_nop 4
	ds_write2st64_b32 v43, v64, v65 offset0:41 offset1:42
	ds_write2st64_b32 v43, v66, v67 offset0:43 offset1:44

; __device__ __forceinline__ float bf2f(u16 h) { return __uint_as_float(((uint32_t)h) << 16); }
; __device__ __forceinline__ float ex2(float x) { return __builtin_amdgcn_exp2f(x); }
; __device__ __forceinline__ float silu(float x) { return x * __builtin_amdgcn_rcpf(1.0f + __expf(-x)); }
; template <int DK, int MODE>
; __device__ void rec_sample_loop(const Params& p, unsigned char* smem, const int rep) {
;     ...
;     {
;       const int i = w, e = lane;
;       float o = 0.f;
; #pragma unroll
;       for (int ww = 0; ww < 8; ++ww) o += redS[(ww * 8 + i) * 64 + e];
;       float ci = 0.f;
; #pragma unroll
;       for (int t = 0; t < 8; ++t) if (t == i) ci = cum[t];
;       o *= ex2(ci);
; #pragma unroll
;       for (int jj = 0; jj < 8; ++jj) if (jj <= i) o += scS[i * 8 + jj] * vS[jj * 64 + e];
;       const int row = row0 + i;
;       const float gv = bf2f(gzv);
;       if (MODE == 0) {
;         const float ssq = wave_sum(o * o);
;         const float val = o * p.ret_head_norm[h * 512 + s * 64 + e] * silu(gv);
;         aout[(size_t)row * 2048 + h * 512 + s * 64 + e] = f2bf(val);
;         if (lane < 2) parts[(size_t)row * 64 + h * 16 + s * 2 + lane] = lane == 0 ? ssq : 0.f;
;       } else {
;         const float y = o + vS[i * 64 + e] * p.ssm_d[h];
;         const float gg = y * silu(gv);
;         const float ssq = wave_sum(gg * gg);
;         aout[(size_t)row * 2048 + h * 64 + e] = f2bf(gg * p.ssm_gate_norm[h * 64 + e]);
;         if (lane < 2) parts[(size_t)row * 64 + (h >> 2) * 8 + (h & 3) * 2 + lane] = lane == 0 ? ssq : 0.f;
;       }
.LBB0_1793:
	s_or_b64 exec, exec, s[48:49]
	v_and_b32_e32 v31, 31, v68
	v_lshlrev_b32_e32 v29, 2, v31
	v_mov_b32_e32 v43, v30
	v_lshl_or_b32 v42, v31, 6, v87
	v_lshl_add_u64 v[42:43], v[42:43], 2, s[94:95]
	v_lshlrev_b32_e32 v40, 16, v134
	v_mul_f32_e32 v29, 0xbfb8aa3b, v40
	v_exp_f32_e32 v29, v29
	ds_read_b32 v43, v130 offset:8192
	v_mov_b32_e32 v103, v30
	v_add_f32_e32 v29, 1.0, v29
	v_rcp_f32_e32 v42, v29
	s_waitcnt vmcnt(16) lgkmcnt(0)
	v_mov_b32_e32 v41, v214
	v_pk_mul_f32 v[40:41], v[42:43], v[40:41]
	s_nop 0
	v_add_f32_e32 v28, v28, v41
	v_mul_f32_e32 v43, v40, v28
	v_mul_f32_e32 v28, v43, v43
	ds_bpermute_b32 v28, v151, v28
	v_ashrrev_i32_e32 v40, 2, v68
	v_lshlrev_b32_e32 v42, 7, v31
	s_waitcnt lgkmcnt(0)
	v_fmac_f32_e32 v28, v43, v43
	ds_bpermute_b32 v29, v152, v28
	s_waitcnt lgkmcnt(0)
	v_add_f32_e32 v28, v28, v29
	ds_bpermute_b32 v29, v153, v28
	s_waitcnt lgkmcnt(0)
	v_add_f32_e32 v41, v28, v29
	ds_bpermute_b32 v44, v154, v41
	v_and_b32_e32 v28, -8, v40
	v_add_u32_e32 v28, v28, v133
	v_ashrrev_i32_e32 v29, 31, v28
	s_waitcnt lgkmcnt(0)
	v_add_f32_e32 v47, v41, v44
	ds_bpermute_b32 v48, v155, v47
	v_lshlrev_b64 v[40:41], 12, v[28:29]
	v_lshl_add_u64 v[44:45], s[0:1], 0, v[40:41]
	s_waitcnt vmcnt(16)
	v_mul_f32_e32 v40, v43, v215
	v_cvt_pk_bf16_f32 v46, v40, s0
	s_waitcnt lgkmcnt(0)
	v_add_f32_e32 v40, v47, v48
	ds_bpermute_b32 v41, v156, v40
	v_mov_b32_e32 v43, v30
	v_lshl_add_u64 v[42:43], v[44:45], 0, v[42:43]
	v_lshl_add_u64 v[42:43], v[42:43], 0, v[102:103]
	global_store_short v[42:43], v46, off
	s_and_saveexec_b64 s[48:49], s[20:21]
	s_cbranch_execz .LBB0_1795
	s_waitcnt lgkmcnt(0)
	v_add_f32_e32 v40, v40, v41
	v_lshlrev_b64 v[28:29], 8, v[28:29]
	v_lshlrev_b32_e32 v31, 3, v31
	v_cndmask_b32_e64 v42, 0, v40, s[22:23]
	v_lshl_add_u64 v[28:29], s[82:83], 0, v[28:29]
	v_and_b32_e32 v40, 0xe0, v31
	v_mov_b32_e32 v41, v30
	v_lshlrev_b32_e32 v31, 3, v68
	v_lshl_add_u64 v[28:29], v[28:29], 0, v[40:41]
	v_and_b32_e32 v40, 24, v31
	v_lshl_add_u64 v[28:29], v[28:29], 0, v[40:41]
	v_lshlrev_b32_e32 v40, 2, v86
	v_lshl_add_u64 v[28:29], v[28:29], 0, v[40:41]
	global_store_dword v[28:29], v42, off

; template <int DK, int MODE>
; __device__ void rec_sample_loop(const Params& p, unsigned char* smem, const int rep) {
;     ...
;       for (int eb = 0; eb < 4; ++eb) {
;         u32x4 sb;
;         sb.x = pack2(sv[par][0][eb][0], sv[par][0][eb][1]);
;         sb.y = pack2(sv[par][0][eb][2], sv[par][0][eb][3]);
;         if (NB == 2) {
;           sb.z = pack2(sv[par][NB - 1][eb][0], sv[par][NB - 1][eb][1]);
;           sb.w = pack2(sv[par][NB - 1][eb][2], sv[par][NB - 1][eb][3]);
;         } else { sb.z = 0u; sb.w = 0u; }
;         const f32x4 o3 = __builtin_amdgcn_mfma_f32_16x16x32_bf16(qa, __builtin_bit_cast(bf16x8, sb),
;                                                                  (f32x4){0.f, 0.f, 0.f, 0.f}, 0, 0, 0);
;         if (g < 2) {
; #pragma unroll
;           for (int r = 0; r < 4; ++r) redS[(w * 8 + 4 * g + r) * 64 + 16 * eb + l15] = o3[r];
;         }
; #pragma unroll
;         for (int db = 0; db < NB; ++db) {
;           f32x4 c = sv[par][db][eb];
;           c[0] *= atot; c[1] *= atot; c[2] *= atot; c[3] *= atot;
;           const f32x4 dn = __builtin_amdgcn_mfma_f32_16x16x32_bf16(kA[db], vB[eb], c, 0, 0, 0);
; #pragma unroll
;           for (int r = 0; r < 4; ++r) s1[(size_t)(dbase + 16 * db + 4 * g + r) * pitch + 16 * eb + l15] = dn[r];
;         }
;       }
.LBB0_1821:
	s_or_b64 exec, exec, s[46:47]
	s_and_b32 s46, s50, 0xfff
	s_nop 3
	v_exp_f32_e32 v70, v43
	s_waitcnt lgkmcnt(3)
	v_cndmask_b32_e64 v55, 0, v55, s[16:17]
	v_cndmask_b32_e64 v54, 0, v54, s[16:17]
	v_cndmask_b32_e64 v53, 0, v53, s[16:17]
	v_cndmask_b32_e64 v52, 0, v52, s[16:17]
	v_add_u32_e32 v68, s46, v74
	v_ashrrev_i32_e32 v69, 31, v68
	v_and_b32_e32 v212, 31, v68
	v_lshlrev_b32_e32 v213, 2, v212
	global_load_dword v214, v213, s[92:93]
	v_lshl_or_b32 v216, v212, 6, v87
	v_mov_b32_e32 v217, 0
	v_lshl_add_u64 v[216:217], v[216:217], 2, s[94:95]
	global_load_dword v215, v[216:217], off
	v_lshlrev_b64 v[120:121], 15, v[68:69]
	v_lshl_add_u64 v[126:127], v[98:99], 0, v[120:121]
	v_pk_mul_f32 v[122:123], v[112:113], v[70:71] op_sel_hi:[1,0]
	v_pk_mul_f32 v[120:121], v[110:111], v[70:71] op_sel_hi:[1,0]
	s_waitcnt lgkmcnt(2)
	v_cndmask_b32_e64 v67, 0, v67, s[16:17]
	v_cndmask_b32_e64 v66, 0, v66, s[16:17]
	v_cndmask_b32_e64 v65, 0, v65, s[16:17]
	v_cndmask_b32_e64 v64, 0, v64, s[16:17]
	v_lshl_add_u64 v[124:125], v[126:127], 0, v[92:93]
	s_nop 0
	v_mfma_f32_16x16x32_bf16 v[64:67], v[52:55], v[64:67], v[120:123]
	s_nop 2
	v_lshl_add_u64 v[120:121], v[126:127], 0, v[88:89]
	v_lshl_add_u64 v[122:123], v[126:127], 0, v[90:91]
	v_lshl_add_u64 v[126:127], v[126:127], 0, v[94:95]
	s_nop 1
	global_store_dword v[120:121], v64, off
	global_store_dword v[122:123], v65, off
	global_store_dword v[124:125], v66, off
	global_store_dword v[126:127], v67, off
	v_cvt_pk_bf16_f32 v64, v106, v107
	v_cvt_pk_bf16_f32 v65, v114, v115
	v_mov_b32_e32 v66, v30
	v_mov_b32_e32 v67, v30
	s_nop 1
	v_mfma_f32_16x16x32_bf16 v[64:67], v[28:31], v[64:67], 0
	s_and_saveexec_b64 s[46:47], s[14:15]
	s_cbranch_execz .LBB0_1823
	v_add_u32_e32 v43, 64, v159
	s_nop 4
	ds_write2st64_b32 v43, v64, v65 offset0:159 offset1:160
	ds_write2st64_b32 v43, v66, v67 offset0:161 offset1:162

; __device__ __forceinline__ float bf2f(u16 h) { return __uint_as_float(((uint32_t)h) << 16); }
; __device__ __forceinline__ float ex2(float x) { return __builtin_amdgcn_exp2f(x); }
; __device__ __forceinline__ float silu(float x) { return x * __builtin_amdgcn_rcpf(1.0f + __expf(-x)); }
; template <int DK, int MODE>
; __device__ void rec_sample_loop(const Params& p, unsigned char* smem, const int rep) {
;     ...
;     {
;       const int i = w, e = lane;
;       float o = 0.f;
; #pragma unroll
;       for (int ww = 0; ww < 8; ++ww) o += redS[(ww * 8 + i) * 64 + e];
;       float ci = 0.f;
; #pragma unroll
;       for (int t = 0; t < 8; ++t) if (t == i) ci = cum[t];
;       o *= ex2(ci);
; #pragma unroll
;       for (int jj = 0; jj < 8; ++jj) if (jj <= i) o += scS[i * 8 + jj] * vS[jj * 64 + e];
;       const int row = row0 + i;
;       const float gv = bf2f(gzv);
;       if (MODE == 0) {
;         const float ssq = wave_sum(o * o);
;         const float val = o * p.ret_head_norm[h * 512 + s * 64 + e] * silu(gv);
;         aout[(size_t)row * 2048 + h * 512 + s * 64 + e] = f2bf(val);
;         if (lane < 2) parts[(size_t)row * 64 + h * 16 + s * 2 + lane] = lane == 0 ? ssq : 0.f;
;       } else {
;         const float y = o + vS[i * 64 + e] * p.ssm_d[h];
;         const float gg = y * silu(gv);
;         const float ssq = wave_sum(gg * gg);
;         aout[(size_t)row * 2048 + h * 64 + e] = f2bf(gg * p.ssm_gate_norm[h * 64 + e]);
;         if (lane < 2) parts[(size_t)row * 64 + (h >> 2) * 8 + (h & 3) * 2 + lane] = lane == 0 ? ssq : 0.f;
;       }
.LBB0_1843:
	s_or_b64 exec, exec, s[46:47]
	v_and_b32_e32 v31, 31, v68
	v_lshlrev_b32_e32 v29, 2, v31
	v_mov_b32_e32 v43, v30
	v_lshl_or_b32 v42, v31, 6, v87
	v_lshl_add_u64 v[42:43], v[42:43], 2, s[94:95]
	v_lshlrev_b32_e32 v40, 16, v164
	v_mul_f32_e32 v29, 0xbfb8aa3b, v40
	v_exp_f32_e32 v29, v29
	ds_read_b32 v43, v130 offset:38400
	v_mov_b32_e32 v103, v30
	v_add_f32_e32 v29, 1.0, v29
	v_rcp_f32_e32 v42, v29
	s_waitcnt vmcnt(16) lgkmcnt(0)
	v_mov_b32_e32 v41, v214
	v_pk_mul_f32 v[40:41], v[42:43], v[40:41]
	s_nop 0
	v_add_f32_e32 v28, v28, v41
	v_mul_f32_e32 v43, v40, v28
	v_mul_f32_e32 v28, v43, v43
	ds_bpermute_b32 v28, v151, v28
	v_ashrrev_i32_e32 v40, 2, v68
	v_lshlrev_b32_e32 v42, 7, v31
	s_waitcnt lgkmcnt(0)
	v_fmac_f32_e32 v28, v43, v43
	ds_bpermute_b32 v29, v152, v28
	s_waitcnt lgkmcnt(0)
	v_add_f32_e32 v28, v28, v29
	ds_bpermute_b32 v29, v153, v28
	s_waitcnt lgkmcnt(0)
	v_add_f32_e32 v41, v28, v29
	ds_bpermute_b32 v44, v154, v41
	v_and_b32_e32 v28, -8, v40
	v_add_u32_e32 v28, v28, v133
	v_ashrrev_i32_e32 v29, 31, v28
	s_waitcnt lgkmcnt(0)
	v_add_f32_e32 v47, v41, v44
	ds_bpermute_b32 v48, v155, v47
	v_lshlrev_b64 v[40:41], 12, v[28:29]
	v_lshl_add_u64 v[44:45], s[0:1], 0, v[40:41]
	s_waitcnt vmcnt(16)
	v_mul_f32_e32 v40, v43, v215
	v_cvt_pk_bf16_f32 v46, v40, s0
	s_waitcnt lgkmcnt(0)
	v_add_f32_e32 v40, v47, v48
	ds_bpermute_b32 v41, v156, v40
	v_mov_b32_e32 v43, v30
	v_lshl_add_u64 v[42:43], v[44:45], 0, v[42:43]
	v_lshl_add_u64 v[42:43], v[42:43], 0, v[102:103]
	global_store_short v[42:43], v46, off
	s_and_saveexec_b64 s[46:47], s[20:21]
	s_cbranch_execz .LBB0_1748
	s_waitcnt lgkmcnt(0)
	v_add_f32_e32 v40, v40, v41
	v_lshlrev_b64 v[28:29], 8, v[28:29]
	v_lshlrev_b32_e32 v31, 3, v31
	v_cndmask_b32_e64 v42, 0, v40, s[22:23]
	v_lshl_add_u64 v[28:29], s[82:83], 0, v[28:29]
	v_and_b32_e32 v40, 0xe0, v31
	v_mov_b32_e32 v41, v30
	v_lshlrev_b32_e32 v31, 3, v68
	v_lshl_add_u64 v[28:29], v[28:29], 0, v[40:41]
	v_and_b32_e32 v40, 24, v31
	v_lshl_add_u64 v[28:29], v[28:29], 0, v[40:41]
	v_lshlrev_b32_e32 v40, 2, v86
	v_lshl_add_u64 v[28:29], v[28:29], 0, v[40:41]
	global_store_dword v[28:29], v42, off
	s_branch .LBB0_1748
